# early L1 invalidate: buffer_inv sc1 issued right after the barrier-arrival atomic (overlaps the wait) instead of after the release poll; late inv kept only on the full-rendezvous leader path
# speedup vs baseline: 1.0187x; 1.0091x over previous
; DEVI unsigned xb_add(unsigned* p, unsigned v) { return __hip_atomic_fetch_add(p, v, __ATOMIC_RELAXED, __HIP_MEMORY_SCOPE_AGENT); }
; DEVI void xcd_barrier(const XcdBarrier& b) {
;     ...
;     const unsigned old = xb_add(&bar[XB_XSUB(b.x)], 1u);
;     const unsigned gen = old / nloc;
;     if (old + 1u == (gen + 1u) * nloc) {
;       __builtin_amdgcn_fence(__ATOMIC_RELEASE, "agent");
;       asm volatile("s_waitcnt vmcnt(0)" ::: "memory");
;       const unsigned og = xb_add(&bar[XB_TOP], 1u);
.LBB0_945:
	s_mov_b64 s[38:39], exec
	v_mbcnt_lo_u32_b32 v0, s38, 0
	v_mbcnt_hi_u32_b32 v0, s39, v0
	v_cmp_eq_u32_e32 vcc, 0, v0
	s_and_saveexec_b64 s[36:37], vcc
	s_cbranch_execz .LBB0_947
	s_bcnt1_i32_b64 s20, s[38:39]
	v_mov_b32_e32 v4, s20
	v_readlane_b32 s20, v242, 22
	v_readlane_b32 s21, v242, 23
	s_nop 4
	global_atomic_add v4, v1, v4, s[20:21] sc0
	buffer_inv sc1

; DEVI unsigned xb_ld(unsigned* p) { return __hip_atomic_load(p, __ATOMIC_RELAXED, __HIP_MEMORY_SCOPE_AGENT); }
; #define XB_SPIN(cond, bar) do { unsigned _sp = 0; while (cond) { __builtin_amdgcn_s_sleep(1); \
;     if ((++_sp & 255u) == 0u) { if (xb_ld(&(bar)[XB_TMO])) break; if (_sp > XB_SPIN_CAP) { atomicAdd(&(bar)[XB_TMO], 1u); break; } } } } while (0)
; DEVI void xcd_barrier(const XcdBarrier& b) {
;     ...
;     } else {
;       XB_SPIN(xb_ld(&bar[XB_XGEN(b.x)]) == gen, bar);
;       __builtin_amdgcn_fence(__ATOMIC_ACQUIRE, "agent");
;       asm volatile("s_waitcnt vmcnt(0)" ::: "memory");
;     }
.LBB0_960:
	s_or_b64 exec, exec, s[38:39]
	s_waitcnt vmcnt(0)
.LBB0_961:
	s_andn2_saveexec_b64 s[26:27], s[36:37]
	s_cbranch_execnz .LBB0_962
	s_getpc_b64 s[98:99]

; DEVI unsigned xb_ld(unsigned* p) { return __hip_atomic_load(p, __ATOMIC_RELAXED, __HIP_MEMORY_SCOPE_AGENT); }
; DEVI unsigned xb_add(unsigned* p, unsigned v) { return __hip_atomic_fetch_add(p, v, __ATOMIC_RELAXED, __HIP_MEMORY_SCOPE_AGENT); }
; #define XB_SPIN(cond, bar) do { unsigned _sp = 0; while (cond) { __builtin_amdgcn_s_sleep(1); \
;     if ((++_sp & 255u) == 0u) { if (xb_ld(&(bar)[XB_TMO])) break; if (_sp > XB_SPIN_CAP) { atomicAdd(&(bar)[XB_TMO], 1u); break; } } } } while (0)
; DEVI void xcd_barrier(const XcdBarrier& b) {
;     ...
;     if (old + 1u == (gen + 1u) * nloc) {
;       __builtin_amdgcn_fence(__ATOMIC_RELEASE, "agent");
;       asm volatile("s_waitcnt vmcnt(0)" ::: "memory");
;       const unsigned og = xb_add(&bar[XB_TOP], 1u);
;       const unsigned tg = og / nx;
;       if (og + 1u == (tg + 1u) * nx) xb_add(&bar[XB_TOPGEN], 1u);
;       else XB_SPIN(xb_ld(&bar[XB_TOPGEN]) == tg, bar);
;       __builtin_amdgcn_fence(__ATOMIC_ACQUIRE, "agent");
;       xb_add(&bar[XB_XGEN(b.x)], 1u);
;       asm volatile("s_waitcnt vmcnt(0)" ::: "memory");
.LBB0_978:
	s_or_b64 exec, exec, s[36:37]
	s_cmp_eq_u32 s101, 0
	s_cbranch_scc0 .Lxb_noinv
	s_waitcnt vmcnt(0)
	buffer_inv sc1
.Lxb_noinv:
	s_mov_b64 s[36:37], exec
	v_mbcnt_lo_u32_b32 v0, s36, 0
	v_mbcnt_hi_u32_b32 v0, s37, v0
	v_cmp_eq_u32_e32 vcc, 0, v0
	s_waitcnt vmcnt(0)
	s_and_saveexec_b64 s[38:39], vcc
	s_cbranch_execnz .LBB0_979
	s_getpc_b64 s[98:99]

; DEVI unsigned xb_add(unsigned* p, unsigned v) { return __hip_atomic_fetch_add(p, v, __ATOMIC_RELAXED, __HIP_MEMORY_SCOPE_AGENT); }
; DEVI void xcd_barrier(const XcdBarrier& b) {
;     ...
;     if (nloc == 0u) { xcd_barrier_complete(bar, b.x, nloc, nx); b.st[0] = nloc; b.st[1] = nx; }
;     const unsigned old = xb_add(&bar[XB_XSUB(b.x)], 1u);
;     const unsigned gen = old / nloc;
;     if (old + 1u == (gen + 1u) * nloc) {
.Lxb_local_leader:
	s_mov_b32 s101, 2
	s_mov_b64 s[36:37], exec
	s_branch .LBB0_978
